# lru1 static schedule + deserialised conv halo loads; LN row/y/gate loads hoisted to one round trip per iteration
# speedup vs baseline: 1.0128x; 1.0128x over previous
.LBB0_111:
	v_ashrrev_i32_e32 v87, 31, v86
	v_add_u32_e32 v110, 1, v86
	v_add_u32_e32 v104, 2, v86
	v_add_u32_e32 v98, 3, v86
	v_lshlrev_b64 v[116:117], 12, v[86:87]
	v_ashrrev_i32_e32 v111, 31, v110
	v_ashrrev_i32_e32 v105, 31, v104
	v_ashrrev_i32_e32 v99, 31, v98
	v_lshlrev_b64 v[112:113], 12, v[110:111]
	v_lshlrev_b64 v[106:107], 12, v[104:105]
	v_lshlrev_b64 v[100:101], 12, v[98:99]
	v_lshl_add_u64 v[130:131], v[4:5], 0, v[116:117]
	global_load_dwordx4 v[80:83], v[130:131], off nt
	global_load_dwordx4 v[76:79], v[130:131], off offset:1024 nt
	global_load_dwordx4 v[72:75], v[130:131], off offset:2048 nt
	global_load_dwordx4 v[68:71], v[130:131], off offset:3072 nt
	v_lshl_add_u64 v[130:131], v[4:5], 0, v[112:113]
	global_load_dwordx4 v[64:67], v[130:131], off nt
	global_load_dwordx4 v[60:63], v[130:131], off offset:1024 nt
	global_load_dwordx4 v[56:59], v[130:131], off offset:2048 nt
	global_load_dwordx4 v[52:55], v[130:131], off offset:3072 nt
	v_lshl_add_u64 v[130:131], v[4:5], 0, v[106:107]
	global_load_dwordx4 v[48:51], v[130:131], off nt
	global_load_dwordx4 v[44:47], v[130:131], off offset:1024 nt
	global_load_dwordx4 v[40:43], v[130:131], off offset:2048 nt
	global_load_dwordx4 v[36:39], v[130:131], off offset:3072 nt
	v_lshl_add_u64 v[130:131], v[4:5], 0, v[100:101]
	global_load_dwordx4 v[32:35], v[130:131], off nt
	global_load_dwordx4 v[28:31], v[130:131], off offset:1024 nt
	global_load_dwordx4 v[24:27], v[130:131], off offset:2048 nt
	global_load_dwordx4 v[20:23], v[130:131], off offset:3072 nt
	v_lshlrev_b64 v[114:115], 11, v[86:87]
	v_lshlrev_b64 v[108:109], 11, v[110:111]
	v_lshlrev_b64 v[102:103], 11, v[104:105]
	v_lshlrev_b64 v[96:97], 11, v[98:99]
	v_cmp_ne_u32_e64 s[38:39], 1, v3
	v_mov_b32_e32 v19, v111
	v_mov_b32_e32 v15, v105
	v_mov_b32_e32 v7, v99
	v_mov_b32_e32 v95, v2
	s_and_b64 vcc, exec, s[38:39]
	s_cbranch_vccnz .LBB0_119
	v_ashrrev_i32_e32 v132, 12, v86
	v_ashrrev_i32_e32 v133, 31, v132
	v_lshl_add_u64 v[132:133], s[12:13], 0, v[132:133]
	v_mov_b64_e32 v[134:135], s[84:85]
	s_movk_i32 s10, 0x3000
	v_mad_u64_u32 v[134:135], s[8:9], v132, s10, v[134:135]
	v_mad_i32_i24 v135, v133, s10, v135
	v_lshl_add_u64 v[134:135], v[134:135], 0, v[94:95]
	s_mov_b64 s[8:9], 0x2000
	v_lshl_add_u64 v[134:135], v[134:135], 0, s[8:9]
	global_load_dwordx4 v[170:173], v[134:135], off
	global_load_dwordx4 v[174:177], v[134:135], off offset:1024
	global_load_dwordx4 v[178:181], v[134:135], off offset:2048
	global_load_dwordx4 v[182:185], v[134:135], off offset:3072
	v_lshl_add_u64 v[136:137], v[0:1], 0, v[114:115]
	global_load_dwordx2 v[138:139], v[136:137], off nt
	global_load_dwordx2 v[140:141], v[136:137], off offset:512 nt
	global_load_dwordx2 v[142:143], v[136:137], off offset:1024 nt
	global_load_dwordx2 v[144:145], v[136:137], off offset:1536 nt
	v_lshl_add_u64 v[136:137], v[0:1], 0, v[108:109]
	global_load_dwordx2 v[146:147], v[136:137], off nt
	global_load_dwordx2 v[148:149], v[136:137], off offset:512 nt
	global_load_dwordx2 v[150:151], v[136:137], off offset:1024 nt
	global_load_dwordx2 v[152:153], v[136:137], off offset:1536 nt
	v_lshl_add_u64 v[136:137], v[0:1], 0, v[102:103]
	global_load_dwordx2 v[154:155], v[136:137], off nt
	global_load_dwordx2 v[156:157], v[136:137], off offset:512 nt
	global_load_dwordx2 v[158:159], v[136:137], off offset:1024 nt
	global_load_dwordx2 v[160:161], v[136:137], off offset:1536 nt
	v_lshl_add_u64 v[136:137], v[0:1], 0, v[96:97]
	global_load_dwordx2 v[162:163], v[136:137], off nt
	global_load_dwordx2 v[164:165], v[136:137], off offset:512 nt
	global_load_dwordx2 v[166:167], v[136:137], off offset:1024 nt
	global_load_dwordx2 v[168:169], v[136:137], off offset:1536 nt
	s_mov_b32 s8, 0x3fb504f3
	s_waitcnt vmcnt(15)
	v_pk_add_f32 v[172:173], v[172:173], 1.0 op_sel_hi:[1,0]
	v_pk_add_f32 v[170:171], v[170:171], 1.0 op_sel_hi:[1,0]
	v_lshlrev_b32_e32 v186, 16, v138
	v_and_b32_e32 v187, 0xffff0000, v138
	v_lshlrev_b32_e32 v188, 16, v139
	v_and_b32_e32 v189, 0xffff0000, v139
	v_pk_mul_f32 v[188:189], v[172:173], v[188:189]
	v_pk_mul_f32 v[186:187], v[170:171], v[186:187]
	v_pk_fma_f32 v[82:83], v[82:83], s[8:9], v[188:189] op_sel_hi:[1,0,1]
	v_pk_fma_f32 v[80:81], v[80:81], s[8:9], v[186:187] op_sel_hi:[1,0,1]
	s_waitcnt vmcnt(14)
	v_pk_add_f32 v[176:177], v[176:177], 1.0 op_sel_hi:[1,0]
	v_pk_add_f32 v[174:175], v[174:175], 1.0 op_sel_hi:[1,0]
	v_lshlrev_b32_e32 v186, 16, v140
	v_and_b32_e32 v187, 0xffff0000, v140
	v_lshlrev_b32_e32 v188, 16, v141
	v_and_b32_e32 v189, 0xffff0000, v141
	v_pk_mul_f32 v[188:189], v[176:177], v[188:189]
	v_pk_mul_f32 v[186:187], v[174:175], v[186:187]
	v_pk_fma_f32 v[78:79], v[78:79], s[8:9], v[188:189] op_sel_hi:[1,0,1]
	v_pk_fma_f32 v[76:77], v[76:77], s[8:9], v[186:187] op_sel_hi:[1,0,1]
	s_waitcnt vmcnt(13)
	v_pk_add_f32 v[180:181], v[180:181], 1.0 op_sel_hi:[1,0]
	v_pk_add_f32 v[178:179], v[178:179], 1.0 op_sel_hi:[1,0]
	v_lshlrev_b32_e32 v186, 16, v142
	v_and_b32_e32 v187, 0xffff0000, v142
	v_lshlrev_b32_e32 v188, 16, v143
	v_and_b32_e32 v189, 0xffff0000, v143
	v_pk_mul_f32 v[188:189], v[180:181], v[188:189]
	v_pk_mul_f32 v[186:187], v[178:179], v[186:187]
	v_pk_fma_f32 v[74:75], v[74:75], s[8:9], v[188:189] op_sel_hi:[1,0,1]
	v_pk_fma_f32 v[72:73], v[72:73], s[8:9], v[186:187] op_sel_hi:[1,0,1]
	s_waitcnt vmcnt(12)
	v_pk_add_f32 v[184:185], v[184:185], 1.0 op_sel_hi:[1,0]
	v_pk_add_f32 v[182:183], v[182:183], 1.0 op_sel_hi:[1,0]
	v_lshlrev_b32_e32 v186, 16, v144
	v_and_b32_e32 v187, 0xffff0000, v144
	v_lshlrev_b32_e32 v188, 16, v145
	v_and_b32_e32 v189, 0xffff0000, v145
	v_pk_mul_f32 v[188:189], v[184:185], v[188:189]
	v_pk_mul_f32 v[186:187], v[182:183], v[186:187]
	v_pk_fma_f32 v[70:71], v[70:71], s[8:9], v[188:189] op_sel_hi:[1,0,1]
	v_pk_fma_f32 v[68:69], v[68:69], s[8:9], v[186:187] op_sel_hi:[1,0,1]
	s_waitcnt vmcnt(11)
	v_lshlrev_b32_e32 v186, 16, v146
	v_and_b32_e32 v187, 0xffff0000, v146
	v_lshlrev_b32_e32 v188, 16, v147
	v_and_b32_e32 v189, 0xffff0000, v147
	v_pk_mul_f32 v[188:189], v[172:173], v[188:189]
	v_pk_mul_f32 v[186:187], v[170:171], v[186:187]
	v_pk_fma_f32 v[66:67], v[66:67], s[8:9], v[188:189] op_sel_hi:[1,0,1]
	v_pk_fma_f32 v[64:65], v[64:65], s[8:9], v[186:187] op_sel_hi:[1,0,1]
	s_waitcnt vmcnt(10)
	v_lshlrev_b32_e32 v186, 16, v148
	v_and_b32_e32 v187, 0xffff0000, v148
	v_lshlrev_b32_e32 v188, 16, v149
	v_and_b32_e32 v189, 0xffff0000, v149
	v_pk_mul_f32 v[188:189], v[176:177], v[188:189]
	v_pk_mul_f32 v[186:187], v[174:175], v[186:187]
	v_pk_fma_f32 v[62:63], v[62:63], s[8:9], v[188:189] op_sel_hi:[1,0,1]
	v_pk_fma_f32 v[60:61], v[60:61], s[8:9], v[186:187] op_sel_hi:[1,0,1]
	s_waitcnt vmcnt(9)
	v_lshlrev_b32_e32 v186, 16, v150
	v_and_b32_e32 v187, 0xffff0000, v150
	v_lshlrev_b32_e32 v188, 16, v151
	v_and_b32_e32 v189, 0xffff0000, v151
	v_pk_mul_f32 v[188:189], v[180:181], v[188:189]
	v_pk_mul_f32 v[186:187], v[178:179], v[186:187]
	v_pk_fma_f32 v[58:59], v[58:59], s[8:9], v[188:189] op_sel_hi:[1,0,1]
	v_pk_fma_f32 v[56:57], v[56:57], s[8:9], v[186:187] op_sel_hi:[1,0,1]
	s_waitcnt vmcnt(8)
	v_lshlrev_b32_e32 v186, 16, v152
	v_and_b32_e32 v187, 0xffff0000, v152
	v_lshlrev_b32_e32 v188, 16, v153
	v_and_b32_e32 v189, 0xffff0000, v153
	v_pk_mul_f32 v[188:189], v[184:185], v[188:189]
	v_pk_mul_f32 v[186:187], v[182:183], v[186:187]
	v_pk_fma_f32 v[54:55], v[54:55], s[8:9], v[188:189] op_sel_hi:[1,0,1]
	v_pk_fma_f32 v[52:53], v[52:53], s[8:9], v[186:187] op_sel_hi:[1,0,1]
	s_waitcnt vmcnt(7)
	v_lshlrev_b32_e32 v186, 16, v154
	v_and_b32_e32 v187, 0xffff0000, v154
	v_lshlrev_b32_e32 v188, 16, v155
	v_and_b32_e32 v189, 0xffff0000, v155
	v_pk_mul_f32 v[188:189], v[172:173], v[188:189]
	v_pk_mul_f32 v[186:187], v[170:171], v[186:187]
	v_pk_fma_f32 v[50:51], v[50:51], s[8:9], v[188:189] op_sel_hi:[1,0,1]
	v_pk_fma_f32 v[48:49], v[48:49], s[8:9], v[186:187] op_sel_hi:[1,0,1]
	s_waitcnt vmcnt(6)
	v_lshlrev_b32_e32 v186, 16, v156
	v_and_b32_e32 v187, 0xffff0000, v156
	v_lshlrev_b32_e32 v188, 16, v157
	v_and_b32_e32 v189, 0xffff0000, v157
	v_pk_mul_f32 v[188:189], v[176:177], v[188:189]
	v_pk_mul_f32 v[186:187], v[174:175], v[186:187]
	v_pk_fma_f32 v[46:47], v[46:47], s[8:9], v[188:189] op_sel_hi:[1,0,1]
	v_pk_fma_f32 v[44:45], v[44:45], s[8:9], v[186:187] op_sel_hi:[1,0,1]
	s_waitcnt vmcnt(5)
	v_lshlrev_b32_e32 v186, 16, v158
	v_and_b32_e32 v187, 0xffff0000, v158
	v_lshlrev_b32_e32 v188, 16, v159
	v_and_b32_e32 v189, 0xffff0000, v159
	v_pk_mul_f32 v[188:189], v[180:181], v[188:189]
	v_pk_mul_f32 v[186:187], v[178:179], v[186:187]
	v_pk_fma_f32 v[42:43], v[42:43], s[8:9], v[188:189] op_sel_hi:[1,0,1]
	v_pk_fma_f32 v[40:41], v[40:41], s[8:9], v[186:187] op_sel_hi:[1,0,1]
	s_waitcnt vmcnt(4)
	v_lshlrev_b32_e32 v186, 16, v160
	v_and_b32_e32 v187, 0xffff0000, v160
	v_lshlrev_b32_e32 v188, 16, v161
	v_and_b32_e32 v189, 0xffff0000, v161
	v_pk_mul_f32 v[188:189], v[184:185], v[188:189]
	v_pk_mul_f32 v[186:187], v[182:183], v[186:187]
	v_pk_fma_f32 v[38:39], v[38:39], s[8:9], v[188:189] op_sel_hi:[1,0,1]
	v_pk_fma_f32 v[36:37], v[36:37], s[8:9], v[186:187] op_sel_hi:[1,0,1]
	s_waitcnt vmcnt(3)
	v_lshlrev_b32_e32 v186, 16, v162
	v_and_b32_e32 v187, 0xffff0000, v162
	v_lshlrev_b32_e32 v188, 16, v163
	v_and_b32_e32 v189, 0xffff0000, v163
	v_pk_mul_f32 v[188:189], v[172:173], v[188:189]
	v_pk_mul_f32 v[186:187], v[170:171], v[186:187]
	v_pk_fma_f32 v[34:35], v[34:35], s[8:9], v[188:189] op_sel_hi:[1,0,1]
	v_pk_fma_f32 v[32:33], v[32:33], s[8:9], v[186:187] op_sel_hi:[1,0,1]
	s_waitcnt vmcnt(2)
	v_lshlrev_b32_e32 v186, 16, v164
	v_and_b32_e32 v187, 0xffff0000, v164
	v_lshlrev_b32_e32 v188, 16, v165
	v_and_b32_e32 v189, 0xffff0000, v165
	v_pk_mul_f32 v[188:189], v[176:177], v[188:189]
	v_pk_mul_f32 v[186:187], v[174:175], v[186:187]
	v_pk_fma_f32 v[30:31], v[30:31], s[8:9], v[188:189] op_sel_hi:[1,0,1]
	v_pk_fma_f32 v[28:29], v[28:29], s[8:9], v[186:187] op_sel_hi:[1,0,1]
	s_waitcnt vmcnt(1)
	v_lshlrev_b32_e32 v186, 16, v166
	v_and_b32_e32 v187, 0xffff0000, v166
	v_lshlrev_b32_e32 v188, 16, v167
	v_and_b32_e32 v189, 0xffff0000, v167
	v_pk_mul_f32 v[188:189], v[180:181], v[188:189]
	v_pk_mul_f32 v[186:187], v[178:179], v[186:187]
	v_pk_fma_f32 v[26:27], v[26:27], s[8:9], v[188:189] op_sel_hi:[1,0,1]
	v_pk_fma_f32 v[24:25], v[24:25], s[8:9], v[186:187] op_sel_hi:[1,0,1]
	s_waitcnt vmcnt(0)
	v_lshlrev_b32_e32 v186, 16, v168
	v_and_b32_e32 v187, 0xffff0000, v168
	v_lshlrev_b32_e32 v188, 16, v169
	v_and_b32_e32 v189, 0xffff0000, v169
	v_pk_mul_f32 v[188:189], v[184:185], v[188:189]
	v_pk_mul_f32 v[186:187], v[182:183], v[186:187]
	v_pk_fma_f32 v[22:23], v[22:23], s[8:9], v[188:189] op_sel_hi:[1,0,1]
	v_pk_fma_f32 v[20:21], v[20:21], s[8:9], v[186:187] op_sel_hi:[1,0,1]

.LBB0_312:
	s_or_b64 exec, exec, s[2:3]
	v_readlane_b32 s2, v248, 7
	v_readlane_b32 s3, v248, 8
	s_lshl_b32 s80, s2, 6
	s_lshl_b64 s[8:9], s[80:81], 2
	v_readlane_b32 s3, v250, 48
	s_add_u32 s86, s3, s8
	v_readlane_b32 s3, v250, 49
	v_writelane_b32 v248, s8, 33
	s_addc_u32 s87, s3, s9
	s_lshl_b32 s14, s2, 10
	s_lshl_b32 s2, s2, 16
	v_readlane_b32 s3, v249, 31
	s_add_u32 s12, s3, s2
	v_readlane_b32 s2, v249, 32
	s_addc_u32 s13, s2, 0
	s_mov_b64 s[38:39], 0
	s_waitcnt lgkmcnt(0)
	s_barrier
	v_writelane_b32 v248, s9, 34
	s_mov_b32 s101, s74
	s_branch .LBB0_314

.LBB0_314:
	s_barrier
	v_mov_b32_e32 v199, v201
	v_mov_b32_e32 v1, s101
	s_add_i32 s101, s101, s26
	s_movk_i32 s2, 0x200
	v_cmp_gt_i32_e32 vcc, s2, v1
	s_mov_b64 s[2:3], -1
	s_and_saveexec_b64 s[40:41], vcc
	s_cbranch_execz .LBB0_313
	v_mov_b32_e32 v4, v197
	v_readlane_b32 s2, v249, 29
	v_lshlrev_b32_e32 v0, 5, v1
	v_ashrrev_i32_e32 v5, 31, v4
	v_readlane_b32 s3, v249, 30
	v_and_b32_e32 v1, 0x7f, v1
	v_cmp_ne_u32_e32 vcc, 0, v1
	v_lshl_add_u64 v[12:13], v[4:5], 1, s[2:3]
	v_mov_b32_e32 v1, 0
	v_mov_b32_e32 v7, 0
	s_and_saveexec_b64 s[2:3], vcc
	s_cbranch_execz .LBB0_321
	v_add_u32_e32 v3, -3, v0
	v_mad_i64_i32 v[8:9], s[8:9], v3, s93, v[12:13]
	global_load_ushort v7, v[8:9], off
.LBB0_321:
	s_or_b64 exec, exec, s[2:3]
	s_and_saveexec_b64 s[2:3], vcc
	s_cbranch_execz .LBB0_323
	v_add_u32_e32 v3, -2, v0
	v_mad_i64_i32 v[8:9], s[8:9], v3, s93, v[12:13]
	global_load_ushort v1, v[8:9], off
.LBB0_323:
	s_or_b64 exec, exec, s[2:3]
	v_mov_b32_e32 v16, 0
	v_mov_b32_e32 v15, 0
	s_and_saveexec_b64 s[2:3], vcc
	s_cbranch_execz .LBB0_325
	v_add_u32_e32 v3, -1, v0
	v_mad_i64_i32 v[8:9], s[8:9], v3, s93, v[12:13]
	global_load_ushort v15, v[8:9], off
.LBB0_325:
	s_or_b64 exec, exec, s[2:3]
	v_or_b32_e32 v3, 1, v0
	v_mad_i64_i32 v[22:23], s[2:3], v3, s93, v[12:13]
	v_or_b32_e32 v3, 2, v0
	v_mad_i64_i32 v[24:25], s[2:3], v3, s93, v[12:13]
	v_or_b32_e32 v3, 3, v0
	v_mad_i64_i32 v[26:27], s[2:3], v3, s93, v[12:13]
	v_or_b32_e32 v3, 4, v0
	v_mad_i64_i32 v[28:29], s[2:3], v3, s93, v[12:13]
	v_or_b32_e32 v3, 5, v0
	v_mad_i64_i32 v[30:31], s[2:3], v3, s93, v[12:13]
	v_or_b32_e32 v3, 6, v0
	v_mad_i64_i32 v[84:85], s[2:3], v3, s93, v[12:13]
	v_or_b32_e32 v3, 7, v0
	v_mad_i64_i32 v[86:87], s[2:3], v3, s93, v[12:13]
	v_or_b32_e32 v3, 8, v0
	v_mad_i64_i32 v[88:89], s[2:3], v3, s93, v[12:13]
	v_or_b32_e32 v3, 9, v0
	v_mad_i64_i32 v[90:91], s[2:3], v3, s93, v[12:13]
	v_or_b32_e32 v3, 10, v0
	v_mad_i64_i32 v[92:93], s[2:3], v3, s93, v[12:13]
	v_or_b32_e32 v3, 11, v0
	v_mad_i64_i32 v[94:95], s[2:3], v3, s93, v[12:13]
	v_or_b32_e32 v3, 12, v0
	v_mad_i64_i32 v[96:97], s[2:3], v3, s93, v[12:13]
	v_or_b32_e32 v3, 13, v0
	v_mad_i64_i32 v[98:99], s[2:3], v3, s93, v[12:13]
	v_or_b32_e32 v3, 14, v0
	v_mad_i64_i32 v[100:101], s[2:3], v3, s93, v[12:13]
	v_or_b32_e32 v3, 15, v0
	v_mad_i64_i32 v[102:103], s[2:3], v3, s93, v[12:13]
	v_or_b32_e32 v3, 16, v0
	v_mad_i64_i32 v[104:105], s[2:3], v3, s93, v[12:13]
	v_or_b32_e32 v3, 17, v0
	v_mad_i64_i32 v[106:107], s[2:3], v3, s93, v[12:13]
	v_or_b32_e32 v3, 18, v0
	v_mad_i64_i32 v[108:109], s[2:3], v3, s93, v[12:13]
	v_or_b32_e32 v3, 19, v0
	v_mad_i64_i32 v[110:111], s[2:3], v3, s93, v[12:13]
	v_or_b32_e32 v3, 20, v0
	v_mad_i64_i32 v[112:113], s[2:3], v3, s93, v[12:13]
	v_or_b32_e32 v3, 21, v0
	v_mad_i64_i32 v[114:115], s[2:3], v3, s93, v[12:13]
	v_or_b32_e32 v3, 22, v0
	v_mad_i64_i32 v[116:117], s[2:3], v3, s93, v[12:13]
	v_or_b32_e32 v3, 23, v0
	v_mad_i64_i32 v[118:119], s[2:3], v3, s93, v[12:13]
	v_or_b32_e32 v3, 24, v0
	v_mad_i64_i32 v[120:121], s[2:3], v3, s93, v[12:13]
	v_or_b32_e32 v3, 25, v0
	v_mad_i64_i32 v[122:123], s[2:3], v3, s93, v[12:13]
	v_or_b32_e32 v3, 26, v0
	v_mad_i64_i32 v[124:125], s[2:3], v3, s93, v[12:13]
	v_or_b32_e32 v3, 27, v0
	v_mad_i64_i32 v[126:127], s[2:3], v3, s93, v[12:13]
	v_or_b32_e32 v3, 28, v0
	v_mad_i64_i32 v[128:129], s[2:3], v3, s93, v[12:13]
	v_or_b32_e32 v3, 29, v0
	v_mad_i64_i32 v[130:131], s[2:3], v3, s93, v[12:13]
	v_or_b32_e32 v3, 30, v0
	v_mad_i64_i32 v[20:21], s[2:3], v0, s93, v[12:13]
	v_mad_i64_i32 v[132:133], s[2:3], v3, s93, v[12:13]
	v_add_u32_e32 v8, s14, v4
	v_readlane_b32 s44, v250, 8
	v_readlane_b32 s2, v248, 7
	v_ashrrev_i32_e32 v9, 31, v8
	v_readlane_b32 s56, v250, 20
	v_readlane_b32 s57, v250, 21
	s_mulk_i32 s2, 0xfd00
	v_readlane_b32 s58, v250, 22
	v_lshl_add_u64 v[32:33], v[8:9], 2, s[56:57]
	v_add_u32_e32 v8, s2, v8
	global_load_dword v17, v[32:33], off
	global_load_dword v19, v[32:33], off offset:1024
	v_ashrrev_i32_e32 v9, 31, v8
	v_readlane_b32 s59, v250, 23
	v_lshlrev_b64 v[8:9], 2, v[8:9]
	v_or_b32_e32 v3, 31, v0
	v_lshl_add_u64 v[34:35], s[58:59], 0, v[8:9]
	global_load_dword v134, v[34:35], off
	global_load_ushort v135, v[20:21], off
	global_load_dword v136, v[32:33], off offset:2048
	global_load_dword v137, v[32:33], off offset:3072
	global_load_ushort v140, v[22:23], off
	global_load_ushort v141, v[24:25], off
	v_readlane_b32 s3, v248, 8
	v_mad_i64_i32 v[12:13], s[2:3], v3, s93, v[12:13]
	v_lshlrev_b32_e32 v3, 6, v4
	v_and_b32_e32 v20, 0xfffff000, v3
	v_bfe_u32 v139, v4, 4, 2
	v_ashrrev_i32_e32 v21, 31, v20
	v_and_b32_e32 v138, 15, v4
	v_lshl_add_u64 v[20:21], v[20:21], 1, s[12:13]
	v_lshlrev_b32_e32 v22, 4, v139
	v_mov_b32_e32 v23, v2
	v_lshl_add_u64 v[20:21], v[20:21], 0, v[22:23]
	v_lshlrev_b32_e32 v24, 7, v138
	v_mov_b32_e32 v25, v2
	v_lshl_add_u64 v[22:23], v[20:21], 0, s[90:91]
	v_lshl_add_u64 v[32:33], v[20:21], 0, v[24:25]
	v_lshl_add_u64 v[34:35], v[22:23], 0, v[24:25]
	global_load_dwordx4 v[80:83], v[32:33], off
	global_load_dwordx4 v[68:71], v[32:33], off offset:64
	global_load_ushort v142, v[26:27], off
	global_load_dwordx4 v[72:75], v[34:35], off
	global_load_dwordx4 v[76:79], v[34:35], off offset:64
	global_load_dwordx4 v[52:55], v[32:33], off offset:2048
	global_load_dwordx4 v[60:63], v[32:33], off offset:2112
	global_load_dwordx4 v[56:59], v[34:35], off offset:2048
	global_load_dwordx4 v[64:67], v[34:35], off offset:2112
	global_load_ushort v143, v[28:29], off
	v_or_b32_e32 v26, 0x1000, v24
	v_mov_b32_e32 v27, v2
	v_lshl_add_u64 v[28:29], v[20:21], 0, v[26:27]
	v_lshl_add_u64 v[26:27], v[22:23], 0, v[26:27]
	global_load_dwordx4 v[40:43], v[28:29], off
	global_load_dwordx4 v[48:51], v[28:29], off offset:64
	global_load_ushort v144, v[30:31], off
	global_load_dwordx4 v[44:47], v[26:27], off
	global_load_dwordx4 v[36:39], v[26:27], off offset:64
	v_or_b32_e32 v24, 0x1800, v24
	v_lshl_add_u64 v[20:21], v[20:21], 0, v[24:25]
	v_lshl_add_u64 v[22:23], v[22:23], 0, v[24:25]
	global_load_dwordx4 v[32:35], v[20:21], off
	global_load_dwordx4 v[28:31], v[20:21], off offset:64
	s_nop 0
	global_load_ushort v84, v[84:85], off
	s_nop 0
	global_load_dwordx4 v[24:27], v[22:23], off
	s_nop 0
	global_load_dwordx4 v[20:23], v[22:23], off offset:64
	s_nop 0
	global_load_ushort v85, v[86:87], off
	s_nop 0
	global_load_ushort v86, v[88:89], off
	global_load_ushort v87, v[90:91], off
	s_nop 0
	global_load_ushort v88, v[92:93], off
	global_load_ushort v89, v[94:95], off
	global_load_ushort v90, v[96:97], off
	global_load_ushort v91, v[98:99], off
	s_nop 0
	global_load_ushort v92, v[100:101], off
	global_load_ushort v93, v[102:103], off
	global_load_ushort v94, v[104:105], off
	global_load_ushort v95, v[106:107], off
	global_load_ushort v96, v[108:109], off
	global_load_ushort v97, v[110:111], off
	global_load_ushort v98, v[112:113], off
	global_load_ushort v99, v[114:115], off
	global_load_ushort v100, v[116:117], off
	global_load_ushort v101, v[118:119], off
	global_load_ushort v102, v[120:121], off
	global_load_ushort v103, v[122:123], off
	global_load_ushort v104, v[124:125], off
	global_load_ushort v105, v[126:127], off
	global_load_ushort v106, v[128:129], off
	global_load_ushort v107, v[130:131], off
	global_load_ushort v108, v[132:133], off
	s_nop 0
	global_load_ushort v12, v[12:13], off
	v_lshlrev_b32_e32 v3, 2, v4
	s_barrier
	v_readlane_b32 s45, v250, 9
	v_readlane_b32 s46, v250, 10
	v_readlane_b32 s47, v250, 11
	v_readlane_b32 s48, v250, 12
	v_readlane_b32 s49, v250, 13
	v_readlane_b32 s50, v250, 14
	v_readlane_b32 s51, v250, 15
	v_readlane_b32 s52, v250, 16
	v_readlane_b32 s53, v250, 17
	v_readlane_b32 s54, v250, 18
	v_readlane_b32 s55, v250, 19
	v_readlane_b32 s44, v250, 24
	v_readlane_b32 s46, v250, 26
	v_readlane_b32 s47, v250, 27
	v_readlane_b32 s48, v250, 28
	v_readlane_b32 s49, v250, 29
	v_readlane_b32 s50, v250, 30
	v_readlane_b32 s51, v250, 31
	v_readlane_b32 s52, v250, 32
	v_readlane_b32 s53, v250, 33
	v_readlane_b32 s54, v250, 34
	v_readlane_b32 s55, v250, 35
	v_readlane_b32 s56, v250, 36
	v_readlane_b32 s57, v250, 37
	v_readlane_b32 s58, v250, 38
	v_readlane_b32 s59, v250, 39
	s_mov_b64 s[42:43], s[46:47]
	s_mov_b64 s[46:47], s[50:51]
	s_mov_b64 s[48:49], s[52:53]
	s_mov_b32 s2, 0xbfb8aa3b
	v_readlane_b32 s45, v250, 25
	s_mov_b64 s[50:51], s[54:55]
	s_mov_b64 s[52:53], s[56:57]
	s_mov_b64 s[54:55], s[58:59]
	s_waitcnt vmcnt(51)
	v_lshlrev_b32_e32 v7, 16, v7
	v_lshlrev_b32_e32 v1, 16, v1
	v_lshlrev_b32_e32 v15, 16, v15
	v_mul_f32_e32 v13, v1, v19
	v_fmac_f32_e32 v13, v7, v17
	s_waitcnt vmcnt(50)
	v_add_f32_e32 v7, v13, v134
	s_waitcnt vmcnt(49)
	v_lshlrev_b32_e32 v13, 16, v135
	s_waitcnt vmcnt(47)
	v_mul_f32_e32 v109, v137, v13
	v_fmac_f32_e32 v109, v15, v136
	v_add_f32_e32 v7, v7, v109
	v_mul_f32_e32 v109, v15, v19
	v_fmac_f32_e32 v109, v1, v17
	v_add_f32_e32 v1, v109, v134
	s_waitcnt vmcnt(46)
	v_lshlrev_b32_e32 v109, 16, v140
	v_mul_f32_e32 v110, v137, v109
	v_fmac_f32_e32 v110, v136, v13
	v_add_f32_e32 v1, v1, v110
	ds_write2st64_b32 v3, v7, v1 offset1:4
	v_mul_f32_e32 v1, v19, v13
	s_waitcnt vmcnt(45)
	v_lshlrev_b32_e32 v7, 16, v141
	v_fmac_f32_e32 v1, v15, v17
	v_mul_f32_e32 v15, v137, v7
	v_add_f32_e32 v1, v1, v134
	v_fmac_f32_e32 v15, v136, v109
	v_add_f32_e32 v1, v1, v15
	v_mul_f32_e32 v15, v19, v109
	v_fmac_f32_e32 v15, v17, v13
	v_add_f32_e32 v13, v15, v134
	s_waitcnt vmcnt(42)
	v_lshlrev_b32_e32 v15, 16, v142
	v_mul_f32_e32 v110, v137, v15
	v_fmac_f32_e32 v110, v136, v7
	v_add_f32_e32 v13, v13, v110
	ds_write2st64_b32 v3, v1, v13 offset0:8 offset1:12
	v_mul_f32_e32 v1, v19, v7
	s_waitcnt vmcnt(35)
	v_lshlrev_b32_e32 v13, 16, v143
	v_fmac_f32_e32 v1, v17, v109
	v_mul_f32_e32 v109, v137, v13
	v_add_f32_e32 v1, v1, v134
	v_fmac_f32_e32 v109, v136, v15
	v_add_f32_e32 v1, v1, v109
	v_mul_f32_e32 v109, v19, v15
	v_fmac_f32_e32 v109, v17, v7
	v_add_f32_e32 v7, v109, v134
	s_waitcnt vmcnt(32)
	v_lshlrev_b32_e32 v109, 16, v144
	v_mul_f32_e32 v110, v137, v109
	v_fmac_f32_e32 v110, v136, v13
	v_add_f32_e32 v7, v7, v110
	ds_write2st64_b32 v3, v1, v7 offset0:16 offset1:20
	v_mul_f32_e32 v1, v19, v13
	s_waitcnt vmcnt(27)
	v_lshlrev_b32_e32 v7, 16, v84
	v_fmac_f32_e32 v1, v17, v15
	v_mul_f32_e32 v15, v137, v7
	v_add_f32_e32 v1, v1, v134
	v_fmac_f32_e32 v15, v136, v109
	v_add_f32_e32 v1, v1, v15
	v_mul_f32_e32 v15, v19, v109
	v_fmac_f32_e32 v15, v17, v13
	v_add_f32_e32 v13, v15, v134
	s_waitcnt vmcnt(24)
	v_lshlrev_b32_e32 v15, 16, v85
	v_mul_f32_e32 v84, v137, v15
	v_fmac_f32_e32 v84, v136, v7
	v_add_f32_e32 v13, v13, v84
	ds_write2st64_b32 v3, v1, v13 offset0:24 offset1:28
	v_mul_f32_e32 v1, v19, v7
	s_waitcnt vmcnt(23)
	v_lshlrev_b32_e32 v13, 16, v86
	v_fmac_f32_e32 v1, v17, v109
	v_mul_f32_e32 v84, v137, v13
	v_add_f32_e32 v1, v1, v134
	v_fmac_f32_e32 v84, v136, v15
	v_add_f32_e32 v1, v1, v84
	v_mul_f32_e32 v84, v19, v15
	v_fmac_f32_e32 v84, v17, v7
	v_add_f32_e32 v7, v84, v134
	s_waitcnt vmcnt(22)
	v_lshlrev_b32_e32 v84, 16, v87
	v_mul_f32_e32 v85, v137, v84
	v_fmac_f32_e32 v85, v136, v13
	v_add_f32_e32 v7, v7, v85
	ds_write2st64_b32 v3, v1, v7 offset0:32 offset1:36
	v_mul_f32_e32 v1, v19, v13
	s_waitcnt vmcnt(21)
	v_lshlrev_b32_e32 v7, 16, v88
	v_fmac_f32_e32 v1, v17, v15
	v_mul_f32_e32 v15, v137, v7
	v_add_f32_e32 v1, v1, v134
	v_fmac_f32_e32 v15, v136, v84
	v_add_f32_e32 v1, v1, v15
	v_mul_f32_e32 v15, v19, v84
	v_fmac_f32_e32 v15, v17, v13
	v_add_f32_e32 v13, v15, v134
	s_waitcnt vmcnt(20)
	v_lshlrev_b32_e32 v15, 16, v89
	v_mul_f32_e32 v85, v137, v15
	v_fmac_f32_e32 v85, v136, v7
	v_add_f32_e32 v13, v13, v85
	ds_write2st64_b32 v3, v1, v13 offset0:40 offset1:44
	v_mul_f32_e32 v1, v19, v7
	s_waitcnt vmcnt(19)
	v_lshlrev_b32_e32 v13, 16, v90
	v_fmac_f32_e32 v1, v17, v84
	v_mul_f32_e32 v84, v137, v13
	v_add_f32_e32 v1, v1, v134
	v_fmac_f32_e32 v84, v136, v15
	v_add_f32_e32 v1, v1, v84
	v_mul_f32_e32 v84, v19, v15
	v_fmac_f32_e32 v84, v17, v7
	v_add_f32_e32 v7, v84, v134
	s_waitcnt vmcnt(18)
	v_lshlrev_b32_e32 v84, 16, v91
	v_mul_f32_e32 v85, v137, v84
	v_fmac_f32_e32 v85, v136, v13
	v_add_f32_e32 v7, v7, v85
	ds_write2st64_b32 v3, v1, v7 offset0:48 offset1:52
	v_mul_f32_e32 v1, v19, v13
	s_waitcnt vmcnt(17)
	v_lshlrev_b32_e32 v7, 16, v92
	v_fmac_f32_e32 v1, v17, v15
	v_mul_f32_e32 v15, v137, v7
	v_add_f32_e32 v1, v1, v134
	v_fmac_f32_e32 v15, v136, v84
	v_add_f32_e32 v1, v1, v15
	v_mul_f32_e32 v15, v19, v84
	v_fmac_f32_e32 v15, v17, v13
	v_add_f32_e32 v13, v15, v134
	s_waitcnt vmcnt(16)
	v_lshlrev_b32_e32 v15, 16, v93
	v_mul_f32_e32 v85, v137, v15
	v_fmac_f32_e32 v85, v136, v7
	v_add_f32_e32 v13, v13, v85
	ds_write2st64_b32 v3, v1, v13 offset0:56 offset1:60
	v_mul_f32_e32 v1, v19, v7
	s_waitcnt vmcnt(15)
	v_lshlrev_b32_e32 v13, 16, v94
	v_fmac_f32_e32 v1, v17, v84
	v_mul_f32_e32 v84, v137, v13
	v_add_f32_e32 v1, v1, v134
	v_fmac_f32_e32 v84, v136, v15
	v_add_f32_e32 v1, v1, v84
	v_mul_f32_e32 v84, v19, v15
	v_fmac_f32_e32 v84, v17, v7
	v_add_f32_e32 v7, v84, v134
	s_waitcnt vmcnt(14)
	v_lshlrev_b32_e32 v84, 16, v95
	v_mul_f32_e32 v85, v137, v84
	v_fmac_f32_e32 v85, v136, v13
	v_add_f32_e32 v7, v7, v85
	ds_write2st64_b32 v3, v1, v7 offset0:64 offset1:68
	v_mul_f32_e32 v1, v19, v13
	s_waitcnt vmcnt(13)
	v_lshlrev_b32_e32 v7, 16, v96
	v_fmac_f32_e32 v1, v17, v15
	v_mul_f32_e32 v15, v137, v7
	v_add_f32_e32 v1, v1, v134
	v_fmac_f32_e32 v15, v136, v84
	v_add_f32_e32 v1, v1, v15
	v_mul_f32_e32 v15, v19, v84
	v_fmac_f32_e32 v15, v17, v13
	v_add_f32_e32 v13, v15, v134
	s_waitcnt vmcnt(12)
	v_lshlrev_b32_e32 v15, 16, v97
	v_mul_f32_e32 v85, v137, v15
	v_fmac_f32_e32 v85, v136, v7
	v_add_f32_e32 v13, v13, v85
	ds_write2st64_b32 v3, v1, v13 offset0:72 offset1:76
	v_mul_f32_e32 v1, v19, v7
	s_waitcnt vmcnt(11)
	v_lshlrev_b32_e32 v13, 16, v98
	v_fmac_f32_e32 v1, v17, v84
	v_mul_f32_e32 v84, v137, v13
	v_add_f32_e32 v1, v1, v134
	v_fmac_f32_e32 v84, v136, v15
	v_add_f32_e32 v1, v1, v84
	v_mul_f32_e32 v84, v19, v15
	v_fmac_f32_e32 v84, v17, v7
	v_add_f32_e32 v7, v84, v134
	s_waitcnt vmcnt(10)
	v_lshlrev_b32_e32 v84, 16, v99
	v_mul_f32_e32 v85, v137, v84
	v_fmac_f32_e32 v85, v136, v13
	v_add_f32_e32 v7, v7, v85
	ds_write2st64_b32 v3, v1, v7 offset0:80 offset1:84
	v_mul_f32_e32 v1, v19, v13
	s_waitcnt vmcnt(9)
	v_lshlrev_b32_e32 v7, 16, v100
	v_fmac_f32_e32 v1, v17, v15
	v_mul_f32_e32 v15, v137, v7
	v_add_f32_e32 v1, v1, v134
	v_fmac_f32_e32 v15, v136, v84
	v_add_f32_e32 v1, v1, v15
	v_mul_f32_e32 v15, v19, v84
	v_fmac_f32_e32 v15, v17, v13
	v_add_f32_e32 v13, v15, v134
	s_waitcnt vmcnt(8)
	v_lshlrev_b32_e32 v15, 16, v101
	v_mul_f32_e32 v85, v137, v15
	v_fmac_f32_e32 v85, v136, v7
	v_add_f32_e32 v13, v13, v85
	ds_write2st64_b32 v3, v1, v13 offset0:88 offset1:92
	v_mul_f32_e32 v1, v19, v7
	s_waitcnt vmcnt(7)
	v_lshlrev_b32_e32 v13, 16, v102
	v_fmac_f32_e32 v1, v17, v84
	v_mul_f32_e32 v84, v137, v13
	v_add_f32_e32 v1, v1, v134
	v_fmac_f32_e32 v84, v136, v15
	v_add_f32_e32 v1, v1, v84
	v_mul_f32_e32 v84, v19, v15
	v_fmac_f32_e32 v84, v17, v7
	v_add_f32_e32 v7, v84, v134
	s_waitcnt vmcnt(6)
	v_lshlrev_b32_e32 v84, 16, v103
	v_mul_f32_e32 v85, v137, v84
	v_fmac_f32_e32 v85, v136, v13
	v_add_f32_e32 v7, v7, v85
	ds_write2st64_b32 v3, v1, v7 offset0:96 offset1:100
	v_mul_f32_e32 v1, v19, v13
	s_waitcnt vmcnt(5)
	v_lshlrev_b32_e32 v7, 16, v104
	v_fmac_f32_e32 v1, v17, v15
	v_mul_f32_e32 v15, v137, v7
	v_add_f32_e32 v1, v1, v134
	v_fmac_f32_e32 v15, v136, v84
	v_add_f32_e32 v1, v1, v15
	v_mul_f32_e32 v15, v19, v84
	v_fmac_f32_e32 v15, v17, v13
	v_add_f32_e32 v13, v15, v134
	s_waitcnt vmcnt(4)
	v_lshlrev_b32_e32 v15, 16, v105
	v_mul_f32_e32 v85, v137, v15
	v_fmac_f32_e32 v85, v136, v7
	v_add_f32_e32 v13, v13, v85
	ds_write2st64_b32 v3, v1, v13 offset0:104 offset1:108
	v_mul_f32_e32 v1, v19, v7
	s_waitcnt vmcnt(3)
	v_lshlrev_b32_e32 v13, 16, v106
	v_fmac_f32_e32 v1, v17, v84
	v_mul_f32_e32 v84, v137, v13
	v_add_f32_e32 v1, v1, v134
	v_fmac_f32_e32 v84, v136, v15
	v_add_f32_e32 v1, v1, v84
	v_mul_f32_e32 v84, v19, v15
	v_fmac_f32_e32 v84, v17, v7
	v_add_f32_e32 v7, v84, v134
	s_waitcnt vmcnt(2)
	v_lshlrev_b32_e32 v84, 16, v107
	v_mul_f32_e32 v85, v137, v84
	v_fmac_f32_e32 v85, v136, v13
	v_add_f32_e32 v7, v7, v85
	ds_write2st64_b32 v3, v1, v7 offset0:112 offset1:116
	v_mul_f32_e32 v1, v19, v13
	s_waitcnt vmcnt(1)
	v_lshlrev_b32_e32 v7, 16, v108
	v_fmac_f32_e32 v1, v17, v15
	v_mul_f32_e32 v15, v137, v7
	v_add_f32_e32 v1, v1, v134
	v_fmac_f32_e32 v15, v136, v84
	v_add_f32_e32 v1, v1, v15
	v_mul_f32_e32 v15, v19, v84
	s_waitcnt vmcnt(0)
	v_lshlrev_b32_e32 v12, 16, v12
	v_fmac_f32_e32 v15, v17, v13
	v_mul_f32_e32 v12, v137, v12
	v_add_f32_e32 v13, v15, v134
	v_fmac_f32_e32 v12, v136, v7
	v_add_f32_e32 v7, v13, v12
	ds_write2st64_b32 v3, v1, v7 offset0:120 offset1:124
	v_and_b32_e32 v1, 0xffffffc0, v4
	v_lshlrev_b32_e32 v7, 2, v1
	v_lshl_add_u32 v7, v138, 10, v7
	v_lshl_or_b32 v7, v139, 5, v7
	s_waitcnt lgkmcnt(0)
	s_barrier
	ds_read_b128 v[84:87], v7
	ds_read_b128 v[88:91], v7 offset:16
	ds_read_b128 v[92:95], v7 offset:128
	ds_read_b128 v[96:99], v7 offset:144
	v_lshlrev_b32_e32 v12, 3, v139
	s_waitcnt lgkmcnt(3)
	v_cvt_pk_bf16_f32 v84, v84, v85
	v_cvt_pk_bf16_f32 v85, v86, v87
	s_waitcnt lgkmcnt(2)
	v_cvt_pk_bf16_f32 v86, v88, v89
	v_cvt_pk_bf16_f32 v87, v90, v91
	s_waitcnt lgkmcnt(0)
	v_cvt_pk_bf16_f32 v90, v96, v97
	v_cvt_pk_bf16_f32 v91, v98, v99
	v_mfma_f32_16x16x32_bf16 v[96:99], v[72:75], v[84:87], 0
	v_cvt_pk_bf16_f32 v88, v92, v93
	v_cvt_pk_bf16_f32 v89, v94, v95
	v_lshl_or_b32 v1, v1, 1, v12
	v_mfma_f32_16x16x32_bf16 v[100:103], v[80:83], v[84:87], 0
	v_lshl_add_u32 v1, v138, 9, v1
	v_add_u32_e32 v15, 0x8000, v1
	v_add_u32_e32 v17, 0xc000, v1
	v_mfma_f32_16x16x32_bf16 v[96:99], v[76:79], v[88:91], v[96:99]
	v_mfma_f32_16x16x32_bf16 v[92:95], v[68:71], v[88:91], v[100:103]
	v_mfma_f32_16x16x32_bf16 v[100:103], v[52:55], v[84:87], 0
	s_nop 5
	v_cvt_pk_bf16_f32 v116, v96, v97
	v_cvt_pk_bf16_f32 v117, v98, v99
	v_cvt_pk_bf16_f32 v12, v92, v93
	v_mfma_f32_16x16x32_bf16 v[104:107], v[56:59], v[84:87], 0
	v_cvt_pk_bf16_f32 v13, v94, v95
	v_mfma_f32_16x16x32_bf16 v[108:111], v[40:43], v[84:87], 0
	v_mfma_f32_16x16x32_bf16 v[96:99], v[32:35], v[84:87], 0
	v_mfma_f32_16x16x32_bf16 v[112:115], v[44:47], v[84:87], 0
	v_mfma_f32_16x16x32_bf16 v[84:87], v[24:27], v[84:87], 0
	v_mfma_f32_16x16x32_bf16 v[100:103], v[60:63], v[88:91], v[100:103]
	v_mfma_f32_16x16x32_bf16 v[104:107], v[64:67], v[88:91], v[104:107]
	v_mfma_f32_16x16x32_bf16 v[108:111], v[48:51], v[88:91], v[108:111]
	s_nop 5
	v_cvt_pk_bf16_f32 v100, v100, v101
	v_cvt_pk_bf16_f32 v101, v102, v103
	v_cvt_pk_bf16_f32 v102, v104, v105
	v_mfma_f32_16x16x32_bf16 v[96:99], v[28:31], v[88:91], v[96:99]
	v_cvt_pk_bf16_f32 v103, v106, v107
	ds_write2_b64 v15, v[12:13], v[100:101] offset1:4
	v_cvt_pk_bf16_f32 v12, v108, v109
	v_mfma_f32_16x16x32_bf16 v[92:95], v[36:39], v[88:91], v[112:115]
	v_cvt_pk_bf16_f32 v13, v110, v111
	ds_write2_b64 v17, v[116:117], v[102:103] offset1:4
	v_mfma_f32_16x16x32_bf16 v[84:87], v[20:23], v[88:91], v[84:87]
	s_nop 0
	v_cvt_pk_bf16_f32 v88, v96, v97
	v_cvt_pk_bf16_f32 v89, v98, v99
	s_nop 1
	v_cvt_pk_bf16_f32 v92, v92, v93
	v_cvt_pk_bf16_f32 v93, v94, v95
	s_nop 0
	v_cvt_pk_bf16_f32 v84, v84, v85
	v_cvt_pk_bf16_f32 v85, v86, v87
	ds_write2_b64 v15, v[12:13], v[88:89] offset0:8 offset1:12
	ds_write2_b64 v17, v[92:93], v[84:85] offset0:8 offset1:12
	ds_read_b128 v[84:87], v7 offset:16384
	ds_read_b128 v[88:91], v7 offset:16400
	ds_read_b128 v[92:95], v7 offset:16512
	ds_read_b128 v[96:99], v7 offset:16528
	v_add_u32_e32 v7, 0xa000, v1
	s_waitcnt lgkmcnt(3)
	v_cvt_pk_bf16_f32 v84, v84, v85
	v_cvt_pk_bf16_f32 v85, v86, v87
	s_waitcnt lgkmcnt(2)
	v_cvt_pk_bf16_f32 v86, v88, v89
	v_cvt_pk_bf16_f32 v87, v90, v91
	s_waitcnt lgkmcnt(1)
	v_cvt_pk_bf16_f32 v88, v92, v93
	v_cvt_pk_bf16_f32 v89, v94, v95
	v_mfma_f32_16x16x32_bf16 v[80:83], v[80:83], v[84:87], 0
	s_waitcnt lgkmcnt(0)
	v_cvt_pk_bf16_f32 v90, v96, v97
	v_cvt_pk_bf16_f32 v91, v98, v99
	v_add_u32_e32 v1, 0xe000, v1
	v_mfma_f32_16x16x32_bf16 v[52:55], v[52:55], v[84:87], 0
	v_mfma_f32_16x16x32_bf16 v[72:75], v[72:75], v[84:87], 0
	v_mfma_f32_16x16x32_bf16 v[56:59], v[56:59], v[84:87], 0
	v_mfma_f32_16x16x32_bf16 v[40:43], v[40:43], v[84:87], 0
	v_mfma_f32_16x16x32_bf16 v[32:35], v[32:35], v[84:87], 0
	v_mfma_f32_16x16x32_bf16 v[44:47], v[44:47], v[84:87], 0
	v_mfma_f32_16x16x32_bf16 v[24:27], v[24:27], v[84:87], 0
	v_mfma_f32_16x16x32_bf16 v[68:71], v[68:71], v[88:91], v[80:83]
	v_mfma_f32_16x16x32_bf16 v[52:55], v[60:63], v[88:91], v[52:55]
	v_mfma_f32_16x16x32_bf16 v[72:75], v[76:79], v[88:91], v[72:75]
	s_nop 5
	v_cvt_pk_bf16_f32 v12, v68, v69
	v_cvt_pk_bf16_f32 v13, v70, v71
	v_mfma_f32_16x16x32_bf16 v[56:59], v[64:67], v[88:91], v[56:59]
	v_mfma_f32_16x16x32_bf16 v[40:43], v[48:51], v[88:91], v[40:43]
	v_cvt_pk_bf16_f32 v48, v72, v73
	v_cvt_pk_bf16_f32 v49, v74, v75
	v_mfma_f32_16x16x32_bf16 v[28:31], v[28:31], v[88:91], v[32:35]
	v_mfma_f32_16x16x32_bf16 v[36:39], v[36:39], v[88:91], v[44:47]
	v_mfma_f32_16x16x32_bf16 v[20:23], v[20:23], v[88:91], v[24:27]
	s_nop 1
	v_cvt_pk_bf16_f32 v44, v52, v53
	v_cvt_pk_bf16_f32 v45, v54, v55
	v_cvt_pk_bf16_f32 v46, v56, v57
	v_cvt_pk_bf16_f32 v47, v58, v59
	ds_write2_b64 v7, v[12:13], v[44:45] offset1:4
	v_cvt_pk_bf16_f32 v12, v40, v41
	v_cvt_pk_bf16_f32 v13, v42, v43
	v_cvt_pk_bf16_f32 v24, v28, v29
	v_cvt_pk_bf16_f32 v25, v30, v31
	ds_write2_b64 v1, v[48:49], v[46:47] offset1:4
	v_cvt_pk_bf16_f32 v32, v36, v37
	v_cvt_pk_bf16_f32 v33, v38, v39
	v_cvt_pk_bf16_f32 v20, v20, v21
	v_cvt_pk_bf16_f32 v21, v22, v23
	ds_write2_b64 v7, v[12:13], v[24:25] offset0:8 offset1:12
	ds_write2_b64 v1, v[32:33], v[20:21] offset0:8 offset1:12
	v_lshl_add_u64 v[12:13], s[48:49], 0, v[8:9]
	s_waitcnt lgkmcnt(0)
	s_barrier
	global_load_dword v17, v[12:13], off
	v_lshl_add_u64 v[12:13], s[42:43], 0, v[8:9]
	v_lshl_add_u64 v[8:9], s[46:47], 0, v[8:9]
	global_load_dword v7, v[12:13], off
	global_load_dword v15, v[8:9], off
	v_ashrrev_i32_e32 v1, 31, v0
	v_lshlrev_b64 v[0:1], 10, v[0:1]
	v_lshl_add_u64 v[0:1], v[4:5], 2, v[0:1]
	v_mov_b32_e32 v12, 1.0
	v_lshl_add_u64 v[0:1], s[24:25], 0, v[0:1]
	s_mov_b64 s[42:43], 0
	s_waitcnt vmcnt(2)
	v_mul_f32_e64 v8, |v17|, s2
	v_exp_f32_e32 v13, v8
	v_max_f32_e64 v8, -v17, -v17
	v_max_f32_e32 v17, 0, v8
	s_mov_b32 s2, 0x3f2aaaab
	v_add_f32_e32 v19, 1.0, v13
	v_add_f32_e32 v8, -1.0, v19
	v_sub_f32_e32 v9, v8, v19
	v_add_f32_e32 v9, 1.0, v9
	v_sub_f32_e32 v8, v13, v8
	v_add_f32_e32 v20, v8, v9
	v_frexp_mant_f32_e32 v21, v19
	v_cvt_f64_f32_e32 v[8:9], v19
	v_frexp_exp_i32_f64_e32 v8, v[8:9]
	v_cmp_gt_f32_e32 vcc, s2, v21
	s_mov_b32 s2, 0x3f317218
	s_nop 0
	v_subbrev_co_u32_e32 v8, vcc, 0, v8, vcc
	v_sub_u32_e32 v9, 0, v8
	v_ldexp_f32 v19, v19, v9
	v_ldexp_f32 v9, v20, v9
	v_add_f32_e32 v20, -1.0, v19
	v_add_f32_e32 v23, 1.0, v19
	v_add_f32_e32 v21, 1.0, v20
	v_add_f32_e32 v24, -1.0, v23
	v_sub_f32_e32 v21, v19, v21
	v_sub_f32_e32 v19, v19, v24
	v_add_f32_e32 v21, v9, v21
	v_add_f32_e32 v9, v9, v19
	v_add_f32_e32 v19, v23, v9
	v_rcp_f32_e32 v24, v19
	v_add_f32_e32 v22, v20, v21
	v_sub_f32_e32 v20, v22, v20
	v_sub_f32_e32 v20, v21, v20
	v_sub_f32_e32 v21, v19, v23
	v_sub_f32_e32 v9, v9, v21
	v_mul_f32_e32 v21, v22, v24
	v_mul_f32_e32 v23, v19, v21
	v_fma_f32 v25, v21, v19, -v23
	v_fmac_f32_e32 v25, v21, v9
	v_add_f32_e32 v26, v23, v25
	v_sub_f32_e32 v27, v22, v26
	v_sub_f32_e32 v22, v22, v27
	v_sub_f32_e32 v23, v26, v23
	v_sub_f32_e32 v22, v22, v26
	v_add_f32_e32 v20, v20, v22
	v_sub_f32_e32 v22, v23, v25
	v_add_f32_e32 v20, v22, v20
	v_add_f32_e32 v22, v27, v20
	v_mul_f32_e32 v23, v24, v22
	v_mul_f32_e32 v25, v19, v23
	v_fma_f32 v19, v23, v19, -v25
	v_fmac_f32_e32 v19, v23, v9
	v_sub_f32_e32 v9, v27, v22
	v_add_f32_e32 v9, v20, v9
	v_add_f32_e32 v20, v25, v19
	v_sub_f32_e32 v26, v22, v20
	v_sub_f32_e32 v22, v22, v26
	v_sub_f32_e32 v25, v20, v25
	v_sub_f32_e32 v20, v22, v20
	v_add_f32_e32 v9, v9, v20
	v_sub_f32_e32 v19, v25, v19
	v_cvt_f32_i32_e32 v8, v8
	v_add_f32_e32 v9, v19, v9
	v_add_f32_e32 v19, v21, v23
	v_add_f32_e32 v9, v26, v9
	v_sub_f32_e32 v20, v19, v21
	v_mul_f32_e32 v9, v24, v9
	v_sub_f32_e32 v20, v23, v20
	v_add_f32_e32 v9, v20, v9
	v_mul_f32_e32 v23, 0x3f317218, v8
	v_add_f32_e32 v20, v19, v9
	v_fma_f32 v24, v8, s2, -v23
	v_mul_f32_e32 v21, v20, v20
	v_fmac_f32_e32 v24, 0xb102e308, v8
	v_sub_f32_e32 v8, v20, v19
	v_fmamk_f32 v22, v21, 0x3e9b6dac, v204
	v_sub_f32_e32 v8, v9, v8
	v_add_f32_e32 v9, v23, v24
	v_fmaak_f32 v22, v21, v22, 0x3f2aaada
	v_sub_f32_e32 v19, v9, v23
	v_ldexp_f32 v23, v20, 1
	v_mul_f32_e32 v20, v20, v21
	v_mul_f32_e32 v20, v20, v22
	v_add_f32_e32 v21, v23, v20
	v_sub_f32_e32 v22, v21, v23
	v_ldexp_f32 v8, v8, 1
	v_sub_f32_e32 v20, v20, v22
	v_add_f32_e32 v8, v8, v20
	v_add_f32_e32 v20, v21, v8
	v_sub_f32_e32 v21, v20, v21
	v_sub_f32_e32 v8, v8, v21
	v_add_f32_e32 v21, v9, v20
	v_sub_f32_e32 v22, v21, v9
	v_sub_f32_e32 v23, v21, v22
	v_sub_f32_e32 v19, v24, v19
	v_sub_f32_e32 v9, v9, v23
	v_sub_f32_e32 v20, v20, v22
	v_add_f32_e32 v9, v20, v9
	v_add_f32_e32 v20, v19, v8
	v_sub_f32_e32 v22, v20, v19
	v_sub_f32_e32 v23, v20, v22
	v_sub_f32_e32 v19, v19, v23
	v_sub_f32_e32 v8, v8, v22
	v_add_f32_e32 v9, v20, v9
	v_add_f32_e32 v8, v8, v19
	v_add_f32_e32 v19, v21, v9
	v_sub_f32_e32 v20, v19, v21
	v_sub_f32_e32 v9, v9, v20
	v_add_f32_e32 v8, v8, v9
	v_add_f32_e32 v8, v19, v8
	v_cmp_neq_f32_e32 vcc, s1, v13
	s_mov_b32 s2, 0x33800000
	v_lshlrev_b32_e32 v20, 1, v4
	v_cndmask_b32_e32 v8, v207, v8, vcc
	v_cmp_ngt_f32_e32 vcc, -1.0, v13
	s_nop 1
	v_cndmask_b32_e32 v8, v208, v8, vcc
	v_cmp_neq_f32_e32 vcc, -1.0, v13
	s_nop 1
	v_cndmask_b32_e32 v8, v209, v8, vcc
	v_cmp_lt_f32_e64 vcc, |v13|, s2
	s_nop 1
	v_cndmask_b32_e32 v8, v8, v13, vcc
	v_add_f32_e32 v19, v17, v8
	s_waitcnt vmcnt(0)

	.amdhsa_kernel _Z14fwd_megakernel6Params
		.amdhsa_group_segment_fixed_size 65556
		.amdhsa_private_segment_fixed_size 0
		.amdhsa_kernarg_size 424
		.amdhsa_user_sgpr_count 2
		.amdhsa_user_sgpr_dispatch_ptr 0
		.amdhsa_user_sgpr_queue_ptr 0
		.amdhsa_user_sgpr_kernarg_segment_ptr 1
		.amdhsa_user_sgpr_dispatch_id 0
		.amdhsa_user_sgpr_kernarg_preload_length 0
		.amdhsa_user_sgpr_kernarg_preload_offset 0
		.amdhsa_user_sgpr_private_segment_size 0
		.amdhsa_uses_dynamic_stack 0
		.amdhsa_enable_private_segment 0
		.amdhsa_system_sgpr_workgroup_id_x 1
		.amdhsa_system_sgpr_workgroup_id_y 0
		.amdhsa_system_sgpr_workgroup_id_z 0
		.amdhsa_system_sgpr_workgroup_info 0
		.amdhsa_system_vgpr_workitem_id 2
		.amdhsa_next_free_vgpr 251
		.amdhsa_next_free_sgpr 102
		.amdhsa_accum_offset 252
		.amdhsa_reserve_vcc 1
		.amdhsa_float_round_mode_32 0
		.amdhsa_float_round_mode_16_64 0
		.amdhsa_float_denorm_mode_32 3
		.amdhsa_float_denorm_mode_16_64 3
		.amdhsa_dx10_clamp 1
		.amdhsa_ieee_mode 1
		.amdhsa_fp16_overflow 0
		.amdhsa_tg_split 0
		.amdhsa_exception_fp_ieee_invalid_op 0
		.amdhsa_exception_fp_denorm_src 0
		.amdhsa_exception_fp_ieee_div_zero 0
		.amdhsa_exception_fp_ieee_overflow 0
		.amdhsa_exception_fp_ieee_underflow 0
		.amdhsa_exception_fp_ieee_inexact 0
		.amdhsa_exception_int_div_zero 0
	.end_amdhsa_kernel

amdhsa.kernels:
  - .agpr_count:     0
    .args:
      - .offset:         0
        .size:           168
        .value_kind:     by_value
      - .offset:         168
        .size:           4
        .value_kind:     hidden_block_count_x
      - .offset:         172
        .size:           4
        .value_kind:     hidden_block_count_y
      - .offset:         176
        .size:           4
        .value_kind:     hidden_block_count_z
      - .offset:         180
        .size:           2
        .value_kind:     hidden_group_size_x
      - .offset:         182
        .size:           2
        .value_kind:     hidden_group_size_y
      - .offset:         184
        .size:           2
        .value_kind:     hidden_group_size_z
      - .offset:         186
        .size:           2
        .value_kind:     hidden_remainder_x
      - .offset:         188
        .size:           2
        .value_kind:     hidden_remainder_y
      - .offset:         190
        .size:           2
        .value_kind:     hidden_remainder_z
      - .offset:         208
        .size:           8
        .value_kind:     hidden_global_offset_x
      - .offset:         216
        .size:           8
        .value_kind:     hidden_global_offset_y
      - .offset:         224
        .size:           8
        .value_kind:     hidden_global_offset_z
      - .offset:         232
        .size:           2
        .value_kind:     hidden_grid_dims
      - .offset:         256
        .size:           8
        .value_kind:     hidden_multigrid_sync_arg
    .group_segment_fixed_size: 65556
    .kernarg_segment_align: 8
    .kernarg_segment_size: 424
    .language:       OpenCL C
    .language_version:
      - 2
      - 0
    .max_flat_workgroup_size: 256
    .name:           _Z14fwd_megakernel6Params
    .private_segment_fixed_size: 0
    .sgpr_count:     108
    .sgpr_spill_count: 165
    .symbol:         _Z14fwd_megakernel6Params.kd
    .uniform_work_group_size: 1
    .uses_dynamic_stack: false
    .vgpr_count:     251
    .vgpr_spill_count: 0
    .wavefront_size: 64
